# combined: rstd fill via LDS-DMA staging + R1 second-round loads hoisted + R3 per-column weight loads hoisted before the MFMA section (on top of static priority)
# speedup vs baseline: 1.0051x; 1.0051x over previous
; #define LAS __attribute__((address_space(3)))
; __device__ __forceinline__ unsigned cvt_pk_bf16(float lo, float hi) { const f32v2_t v = {lo, hi}; const bf16v2_t r = __builtin_convertvector(v, bf16v2_t); return __builtin_bit_cast(unsigned, r); }
; __device__ __forceinline__ void unpack8(const u32x4 w, float* f) { f[0] = bf_lo(w.x); f[1] = bf_hi(w.x); f[2] = bf_lo(w.y); f[3] = bf_hi(w.y); f[4] = bf_lo(w.z); f[5] = bf_hi(w.z); f[6] = bf_lo(w.w); f[7] = bf_hi(w.w); }
; __device__ __forceinline__ void r3_item(const bf16_t* __restrict__ proj, const bf16_t* __restrict__ projT, const bf16_t* __restrict__ st, bf16_t* ro, ...
;     ...
;     __syncthreads();
; #pragma unroll
;     for (int q = 0; q < 4; ++q) { float s1 = 0.f, s2 = 0.f; const int n = 32 * q + c;
; #pragma unroll
;         for (int k = 0; k < 8; ++k) { s1 += stat[(k * 128 + n) * 2]; s2 += stat[(k * 128 + n) * 2 + 1]; }
;         const float mu = s1 * (1.0f / 256.0f); float var = s2 * (1.0f / 256.0f) - mu * mu; var = var < 0.f ? 0.f : var; const float rs = rsqrtf(var + EPS);
; #pragma unroll
;         for (int g4 = 0; g4 < 4; ++g4) { u32x2 pw; pw.x = cvt_pk_bf16((acc[q][4 * g4] - mu) * rs, (acc[q][4 * g4 + 1] - mu) * rs); pw.y = cvt_pk_bf16((acc[q][4 * g4 + 2] - mu) * rs, (acc[q][4 * g4 + 3] - mu) * rs);
;             *(LAS u32x2*)(Ol + n * OL_STRIDE + 32 * w + 8 * g4 + 4 * hh) = pw; } }
;     __syncthreads();
; #pragma unroll
;     for (int it = 0; it < 8; ++it) { const int id = tid + NTHREADS * it, tq = id >> 5, d8 = (id & 31) * 8;
;         float y[8], rg[8], o[8]; unpack8(*(const LAS u32x4*)(Ol + tq * OL_STRIDE + d8), y);
;         unpack8(__builtin_nontemporal_load((const u32x4*)(proj + (size_t)(tok0 + tq) * NPROJ + 2048 + h * 256 + d8)), rg);
;         const f32x4 g0 = *(const f32x4*)(gn + h * 256 + d8), g1 = *(const f32x4*)(gn + h * 256 + d8 + 4);
.LBB0_484:
	s_or_b64 exec, exec, s[4:5]
	v_and_b32_e32 v72, 0xf8, v249
	v_lshlrev_b32_e32 v72, 1, v72
	v_mov_b32_e32 v73, 0
	v_ashrrev_i32_e32 v74, 5, v247
	v_add_u32_e32 v74, s6, v74
	v_mov_b64_e32 v[76:77], s[40:41]
	s_lshl_b32 s96, s58, 1
	s_add_u32 s96, s96, s23
	s_mov_b32 s97, 0
	v_mad_i64_i32 v[76:77], s[98:99], v74, s18, v[76:77]
	v_lshl_add_u64 v[76:77], v[76:77], 0, s[96:97]
	v_lshl_add_u64 v[76:77], v[76:77], 0, v[72:73]
	s_mov_b32 s96, 0x28000
	global_load_dwordx4 v[80:83], v[76:77], off nt
	v_lshl_add_u64 v[76:77], v[76:77], 0, s[96:97]
	global_load_dwordx4 v[84:87], v[76:77], off nt
	v_lshl_add_u64 v[76:77], v[76:77], 0, s[96:97]
	global_load_dwordx4 v[88:91], v[76:77], off nt
	v_lshl_add_u64 v[76:77], v[76:77], 0, s[96:97]
	global_load_dwordx4 v[92:95], v[76:77], off nt
	v_lshl_add_u64 v[76:77], v[76:77], 0, s[96:97]
	global_load_dwordx4 v[96:99], v[76:77], off nt
	v_lshl_add_u64 v[76:77], v[76:77], 0, s[96:97]
	global_load_dwordx4 v[100:103], v[76:77], off nt
	v_lshl_add_u64 v[76:77], v[76:77], 0, s[96:97]
	global_load_dwordx4 v[104:107], v[76:77], off nt
	v_lshl_add_u64 v[76:77], v[76:77], 0, s[96:97]
	global_load_dwordx4 v[108:111], v[76:77], off nt
	s_lshl_b32 s96, s58, 2
	s_add_u32 s96, s14, s96
	s_addc_u32 s97, s46, 0
	v_and_b32_e32 v120, 0xf8, v249
	v_lshlrev_b32_e32 v120, 2, v120
	global_load_dwordx4 v[112:115], v120, s[96:97] offset:16
	global_load_dwordx4 v[116:119], v120, s[96:97]
	s_add_u32 s4, s30, s42
	s_addc_u32 s5, s31, s43
	s_add_u32 s4, s4, 0x1c240000
	s_addc_u32 s5, s5, 0
	s_lshl_b32 s7, s44, 1
	s_add_i32 s10, s7, 0
	s_add_i32 s7, 0, 0x19800
	v_add_u32_e32 v0, s7, v0
	s_waitcnt lgkmcnt(0)
	s_barrier
	ds_read2st64_b64 v[66:69], v0 offset1:2
	s_waitcnt lgkmcnt(0)
	v_pk_add_f32 v[66:67], v[66:67], 0 op_sel_hi:[1,0]
	s_nop 0
	v_pk_add_f32 v[70:71], v[66:67], v[68:69]
	ds_read2st64_b64 v[66:69], v0 offset0:4 offset1:6
	s_waitcnt lgkmcnt(0)
	v_pk_add_f32 v[66:67], v[70:71], v[66:67]
	s_nop 0
	v_pk_add_f32 v[70:71], v[66:67], v[68:69]
	ds_read2st64_b64 v[66:69], v0 offset0:8 offset1:10
	s_waitcnt lgkmcnt(0)
	v_pk_add_f32 v[66:67], v[70:71], v[66:67]
	s_nop 0
	v_pk_add_f32 v[70:71], v[66:67], v[68:69]
	ds_read2st64_b64 v[66:69], v0 offset0:12 offset1:14
	s_waitcnt lgkmcnt(0)
	v_pk_add_f32 v[66:67], v[70:71], v[66:67]
	s_nop 0
	v_pk_add_f32 v[66:67], v[66:67], v[68:69]
	s_nop 0
	v_pk_mul_f32 v[66:67], v[66:67], s[66:67] op_sel_hi:[1,0]
	s_nop 0
	v_fma_f32 v0, -v66, v66, v67
	v_cmp_ngt_f32_e32 vcc, 0, v0
	v_pk_add_f32 v[50:51], v[50:51], v[66:67] op_sel_hi:[1,0] neg_lo:[0,1] neg_hi:[0,1]
	v_pk_add_f32 v[52:53], v[52:53], v[66:67] op_sel_hi:[1,0] neg_lo:[0,1] neg_hi:[0,1]
	v_cndmask_b32_e32 v0, 0, v0, vcc
	v_add_f32_e32 v0, 0x358637bd, v0
	v_cmp_gt_f32_e32 vcc, s65, v0
	v_mul_f32_e32 v68, 0x4b800000, v0
	s_nop 0
	v_cndmask_b32_e32 v0, v0, v68, vcc
	v_rsq_f32_e32 v0, v0
	s_nop 0
	v_mul_f32_e32 v68, 0x45800000, v0
	v_cndmask_b32_e32 v0, v0, v68, vcc
	v_pk_mul_f32 v[50:51], v[50:51], v[0:1] op_sel_hi:[1,0]
	v_pk_mul_f32 v[52:53], v[52:53], v[0:1] op_sel_hi:[1,0]
	v_cvt_pk_bf16_f32 v50, v50, v51
	v_cvt_pk_bf16_f32 v51, v52, v53
	v_pk_add_f32 v[52:53], v[54:55], v[66:67] op_sel_hi:[1,0] neg_lo:[0,1] neg_hi:[0,1]
	v_pk_add_f32 v[54:55], v[56:57], v[66:67] op_sel_hi:[1,0] neg_lo:[0,1] neg_hi:[0,1]
	v_mul_u32_u24_e32 v68, 0x210, v250
	v_pk_mul_f32 v[52:53], v[52:53], v[0:1] op_sel_hi:[1,0]
	v_pk_mul_f32 v[54:55], v[54:55], v[0:1] op_sel_hi:[1,0]
	v_add3_u32 v68, s10, v252, v68
	v_cvt_pk_bf16_f32 v52, v52, v53
	v_cvt_pk_bf16_f32 v53, v54, v55
	ds_write2_b64 v68, v[50:51], v[52:53] offset1:2
	v_pk_add_f32 v[50:51], v[58:59], v[66:67] op_sel_hi:[1,0] neg_lo:[0,1] neg_hi:[0,1]
	v_pk_add_f32 v[52:53], v[60:61], v[66:67] op_sel_hi:[1,0] neg_lo:[0,1] neg_hi:[0,1]
	v_pk_mul_f32 v[50:51], v[50:51], v[0:1] op_sel_hi:[1,0]
	v_pk_mul_f32 v[52:53], v[52:53], v[0:1] op_sel_hi:[1,0]
	v_cvt_pk_bf16_f32 v50, v50, v51
	v_cvt_pk_bf16_f32 v51, v52, v53
	v_pk_add_f32 v[52:53], v[62:63], v[66:67] op_sel_hi:[1,0] neg_lo:[0,1] neg_hi:[0,1]
	v_pk_add_f32 v[54:55], v[64:65], v[66:67] op_sel_hi:[1,0] neg_lo:[0,1] neg_hi:[0,1]
	v_pk_mul_f32 v[52:53], v[52:53], v[0:1] op_sel_hi:[1,0]
	v_pk_mul_f32 v[54:55], v[54:55], v[0:1] op_sel_hi:[1,0]
	v_cvt_pk_bf16_f32 v52, v52, v53
	v_cvt_pk_bf16_f32 v53, v54, v55
	ds_write2_b64 v68, v[50:51], v[52:53] offset0:4 offset1:6
	v_lshl_add_u32 v0, v229, 3, s7
	ds_read2st64_b64 v[50:53], v0 offset1:2
	s_waitcnt lgkmcnt(0)
	v_pk_add_f32 v[50:51], v[50:51], 0 op_sel_hi:[1,0]
	s_nop 0
	v_pk_add_f32 v[54:55], v[50:51], v[52:53]
	ds_read2st64_b64 v[50:53], v0 offset0:4 offset1:6
	s_waitcnt lgkmcnt(0)
	v_pk_add_f32 v[50:51], v[54:55], v[50:51]
	s_nop 0
	v_pk_add_f32 v[54:55], v[50:51], v[52:53]
	ds_read2st64_b64 v[50:53], v0 offset0:8 offset1:10
	s_waitcnt lgkmcnt(0)
	v_pk_add_f32 v[50:51], v[54:55], v[50:51]
	s_nop 0
	v_pk_add_f32 v[54:55], v[50:51], v[52:53]
	ds_read2st64_b64 v[50:53], v0 offset0:12 offset1:14
	s_waitcnt lgkmcnt(0)
; #define LAS __attribute__((address_space(3)))
; __device__ __forceinline__ unsigned cvt_pk_bf16(float lo, float hi) { const f32v2_t v = {lo, hi}; const bf16v2_t r = __builtin_convertvector(v, bf16v2_t); return __builtin_bit_cast(unsigned, r); }
; __device__ __forceinline__ void r3_item(const bf16_t* __restrict__ proj, const bf16_t* __restrict__ projT, const bf16_t* __restrict__ st, bf16_t* ro, ...
;     ...
;     for (int q = 0; q < 4; ++q) { float s1 = 0.f, s2 = 0.f; const int n = 32 * q + c;
; #pragma unroll
;         for (int k = 0; k < 8; ++k) { s1 += stat[(k * 128 + n) * 2]; s2 += stat[(k * 128 + n) * 2 + 1]; }
;         const float mu = s1 * (1.0f / 256.0f); float var = s2 * (1.0f / 256.0f) - mu * mu; var = var < 0.f ? 0.f : var; const float rs = rsqrtf(var + EPS);
; #pragma unroll
;         for (int g4 = 0; g4 < 4; ++g4) { u32x2 pw; pw.x = cvt_pk_bf16((acc[q][4 * g4] - mu) * rs, (acc[q][4 * g4 + 1] - mu) * rs); pw.y = cvt_pk_bf16((acc[q][4 * g4 + 2] - mu) * rs, (acc[q][4 * g4 + 3] - mu) * rs);
;             *(LAS u32x2*)(Ol + n * OL_STRIDE + 32 * w + 8 * g4 + 4 * hh) = pw; } }
	v_pk_add_f32 v[50:51], v[54:55], v[50:51]
	s_nop 0
	v_pk_add_f32 v[50:51], v[50:51], v[52:53]
	s_nop 0
	v_pk_mul_f32 v[50:51], v[50:51], s[66:67] op_sel_hi:[1,0]
	s_nop 0
	v_fma_f32 v0, -v50, v50, v51
	v_cmp_ngt_f32_e32 vcc, 0, v0
	v_pk_add_f32 v[34:35], v[34:35], v[50:51] op_sel_hi:[1,0] neg_lo:[0,1] neg_hi:[0,1]
	v_pk_add_f32 v[36:37], v[36:37], v[50:51] op_sel_hi:[1,0] neg_lo:[0,1] neg_hi:[0,1]
	v_cndmask_b32_e32 v0, 0, v0, vcc
	v_add_f32_e32 v0, 0x358637bd, v0
	v_cmp_gt_f32_e32 vcc, s65, v0
	v_mul_f32_e32 v52, 0x4b800000, v0
	s_nop 0
	v_cndmask_b32_e32 v0, v0, v52, vcc
	v_rsq_f32_e32 v0, v0
	s_nop 0
	v_mul_f32_e32 v52, 0x45800000, v0
	v_cndmask_b32_e32 v0, v0, v52, vcc
	v_pk_mul_f32 v[34:35], v[34:35], v[0:1] op_sel_hi:[1,0]
	v_pk_mul_f32 v[36:37], v[36:37], v[0:1] op_sel_hi:[1,0]
	v_cvt_pk_bf16_f32 v34, v34, v35
	v_cvt_pk_bf16_f32 v35, v36, v37
	v_pk_add_f32 v[36:37], v[38:39], v[50:51] op_sel_hi:[1,0] neg_lo:[0,1] neg_hi:[0,1]
	v_pk_add_f32 v[38:39], v[40:41], v[50:51] op_sel_hi:[1,0] neg_lo:[0,1] neg_hi:[0,1]
	v_pk_mul_f32 v[36:37], v[36:37], v[0:1] op_sel_hi:[1,0]
	v_pk_mul_f32 v[38:39], v[38:39], v[0:1] op_sel_hi:[1,0]
	v_cvt_pk_bf16_f32 v36, v36, v37
	v_cvt_pk_bf16_f32 v37, v38, v39
	v_add_u32_e32 v40, 0x4000, v68
	ds_write2_b64 v40, v[34:35], v[36:37] offset0:64 offset1:66
	v_pk_add_f32 v[34:35], v[42:43], v[50:51] op_sel_hi:[1,0] neg_lo:[0,1] neg_hi:[0,1]
	v_pk_add_f32 v[36:37], v[44:45], v[50:51] op_sel_hi:[1,0] neg_lo:[0,1] neg_hi:[0,1]
	v_pk_mul_f32 v[34:35], v[34:35], v[0:1] op_sel_hi:[1,0]
	v_pk_mul_f32 v[36:37], v[36:37], v[0:1] op_sel_hi:[1,0]
	v_cvt_pk_bf16_f32 v34, v34, v35
	v_cvt_pk_bf16_f32 v35, v36, v37
	v_pk_add_f32 v[36:37], v[46:47], v[50:51] op_sel_hi:[1,0] neg_lo:[0,1] neg_hi:[0,1]
	v_pk_add_f32 v[38:39], v[48:49], v[50:51] op_sel_hi:[1,0] neg_lo:[0,1] neg_hi:[0,1]
	v_pk_mul_f32 v[36:37], v[36:37], v[0:1] op_sel_hi:[1,0]
	v_pk_mul_f32 v[38:39], v[38:39], v[0:1] op_sel_hi:[1,0]
	v_cvt_pk_bf16_f32 v36, v36, v37
	v_cvt_pk_bf16_f32 v37, v38, v39
	ds_write2_b64 v40, v[34:35], v[36:37] offset0:68 offset1:70
	v_lshl_add_u32 v0, v227, 3, s7
	ds_read2st64_b64 v[34:37], v0 offset1:2
	s_waitcnt lgkmcnt(0)
	v_pk_add_f32 v[34:35], v[34:35], 0 op_sel_hi:[1,0]
	s_nop 0
	v_pk_add_f32 v[38:39], v[34:35], v[36:37]
	ds_read2st64_b64 v[34:37], v0 offset0:4 offset1:6
	s_waitcnt lgkmcnt(0)
	v_pk_add_f32 v[34:35], v[38:39], v[34:35]
	s_nop 0
	v_pk_add_f32 v[38:39], v[34:35], v[36:37]
	ds_read2st64_b64 v[34:37], v0 offset0:8 offset1:10
	s_waitcnt lgkmcnt(0)
	v_pk_add_f32 v[34:35], v[38:39], v[34:35]
	s_nop 0
	v_pk_add_f32 v[38:39], v[34:35], v[36:37]
	ds_read2st64_b64 v[34:37], v0 offset0:12 offset1:14
	s_waitcnt lgkmcnt(0)
	v_pk_add_f32 v[34:35], v[38:39], v[34:35]
	s_nop 0
	v_pk_add_f32 v[34:35], v[34:35], v[36:37]
	s_nop 0
	v_pk_mul_f32 v[34:35], v[34:35], s[66:67] op_sel_hi:[1,0]
	s_nop 0
	v_fma_f32 v0, -v34, v34, v35
	v_cmp_ngt_f32_e32 vcc, 0, v0
	v_pk_add_f32 v[18:19], v[18:19], v[34:35] op_sel_hi:[1,0] neg_lo:[0,1] neg_hi:[0,1]
	v_pk_add_f32 v[20:21], v[20:21], v[34:35] op_sel_hi:[1,0] neg_lo:[0,1] neg_hi:[0,1]
	v_cndmask_b32_e32 v0, 0, v0, vcc
	v_add_f32_e32 v0, 0x358637bd, v0
	v_cmp_gt_f32_e32 vcc, s65, v0
	v_mul_f32_e32 v36, 0x4b800000, v0
	s_nop 0
	v_cndmask_b32_e32 v0, v0, v36, vcc
	v_rsq_f32_e32 v0, v0
	s_nop 0
	v_mul_f32_e32 v36, 0x45800000, v0
	v_cndmask_b32_e32 v0, v0, v36, vcc
	v_pk_mul_f32 v[18:19], v[18:19], v[0:1] op_sel_hi:[1,0]
	v_pk_mul_f32 v[20:21], v[20:21], v[0:1] op_sel_hi:[1,0]
	v_cvt_pk_bf16_f32 v18, v18, v19
	v_cvt_pk_bf16_f32 v19, v20, v21
	v_pk_add_f32 v[20:21], v[22:23], v[34:35] op_sel_hi:[1,0] neg_lo:[0,1] neg_hi:[0,1]
	v_pk_add_f32 v[22:23], v[24:25], v[34:35] op_sel_hi:[1,0] neg_lo:[0,1] neg_hi:[0,1]
	v_pk_mul_f32 v[20:21], v[20:21], v[0:1] op_sel_hi:[1,0]
	v_pk_mul_f32 v[22:23], v[22:23], v[0:1] op_sel_hi:[1,0]
	v_cvt_pk_bf16_f32 v20, v20, v21
	v_cvt_pk_bf16_f32 v21, v22, v23
	v_add_u32_e32 v24, 0x8000, v68
	ds_write2_b64 v24, v[18:19], v[20:21] offset0:128 offset1:130
	v_pk_add_f32 v[18:19], v[26:27], v[34:35] op_sel_hi:[1,0] neg_lo:[0,1] neg_hi:[0,1]
	v_pk_add_f32 v[20:21], v[28:29], v[34:35] op_sel_hi:[1,0] neg_lo:[0,1] neg_hi:[0,1]
	v_pk_mul_f32 v[18:19], v[18:19], v[0:1] op_sel_hi:[1,0]
	v_pk_mul_f32 v[20:21], v[20:21], v[0:1] op_sel_hi:[1,0]
	v_cvt_pk_bf16_f32 v18, v18, v19
	v_cvt_pk_bf16_f32 v19, v20, v21
	v_pk_add_f32 v[20:21], v[30:31], v[34:35] op_sel_hi:[1,0] neg_lo:[0,1] neg_hi:[0,1]
	v_pk_add_f32 v[22:23], v[32:33], v[34:35] op_sel_hi:[1,0] neg_lo:[0,1] neg_hi:[0,1]
	v_pk_mul_f32 v[20:21], v[20:21], v[0:1] op_sel_hi:[1,0]
	v_pk_mul_f32 v[22:23], v[22:23], v[0:1] op_sel_hi:[1,0]
	v_cvt_pk_bf16_f32 v20, v20, v21
	v_cvt_pk_bf16_f32 v21, v22, v23
	ds_write2_b64 v24, v[18:19], v[20:21] offset0:132 offset1:134
	v_lshl_add_u32 v0, v210, 3, s7
	ds_read2st64_b64 v[18:21], v0 offset1:2
	s_lshl_b32 s7, s58, 2
	s_add_u32 s10, s14, s7
	s_addc_u32 s11, s46, 0
	s_lshl_b32 s58, s58, 1
	s_waitcnt lgkmcnt(0)
	v_pk_add_f32 v[18:19], v[18:19], 0 op_sel_hi:[1,0]
	s_add_i32 s27, s27, s52
	v_pk_add_f32 v[22:23], v[18:19], v[20:21]
	ds_read2st64_b64 v[18:21], v0 offset0:4 offset1:6
	s_add_i32 s25, s25, s22
	s_add_u32 s0, s0, s54
	s_addc_u32 s1, s1, s55
	s_cmpk_gt_i32 s27, 0x1ff
	s_waitcnt lgkmcnt(0)
	v_pk_add_f32 v[18:19], v[22:23], v[18:19]
	s_nop 0
	v_pk_add_f32 v[22:23], v[18:19], v[20:21]
	ds_read2st64_b64 v[18:21], v0 offset0:8 offset1:10
	s_waitcnt lgkmcnt(0)
	v_pk_add_f32 v[18:19], v[22:23], v[18:19]
	s_nop 0
	v_pk_add_f32 v[22:23], v[18:19], v[20:21]
	ds_read2st64_b64 v[18:21], v0 offset0:12 offset1:14
	s_waitcnt lgkmcnt(0)
; #define LAS __attribute__((address_space(3)))
; __device__ __forceinline__ unsigned cvt_pk_bf16(float lo, float hi) { const f32v2_t v = {lo, hi}; const bf16v2_t r = __builtin_convertvector(v, bf16v2_t); return __builtin_bit_cast(unsigned, r); }
; __device__ __forceinline__ float sigmoidf_(float x) { return __builtin_amdgcn_rcpf(1.0f + __expf(-x)); }
; __device__ __forceinline__ void unpack8(const u32x4 w, float* f) { f[0] = bf_lo(w.x); f[1] = bf_hi(w.x); f[2] = bf_lo(w.y); f[3] = bf_hi(w.y); f[4] = bf_lo(w.z); f[5] = bf_hi(w.z); f[6] = bf_lo(w.w); f[7] = bf_hi(w.w); }
; __device__ __forceinline__ u32x4 pack8(const float* f) { u32x4 w; w.x = cvt_pk_bf16(f[0], f[1]); w.y = cvt_pk_bf16(f[2], f[3]); w.z = cvt_pk_bf16(f[4], f[5]); w.w = cvt_pk_bf16(f[6], f[7]); return w; }
; __device__ __forceinline__ void r3_item(const bf16_t* __restrict__ proj, const bf16_t* __restrict__ projT, const bf16_t* __restrict__ st, bf16_t* ro, ...
;     ...
;     for (int q = 0; q < 4; ++q) { float s1 = 0.f, s2 = 0.f; const int n = 32 * q + c;
; #pragma unroll
;         for (int k = 0; k < 8; ++k) { s1 += stat[(k * 128 + n) * 2]; s2 += stat[(k * 128 + n) * 2 + 1]; }
;         const float mu = s1 * (1.0f / 256.0f); float var = s2 * (1.0f / 256.0f) - mu * mu; var = var < 0.f ? 0.f : var; const float rs = rsqrtf(var + EPS);
; #pragma unroll
;         for (int g4 = 0; g4 < 4; ++g4) { u32x2 pw; pw.x = cvt_pk_bf16((acc[q][4 * g4] - mu) * rs, (acc[q][4 * g4 + 1] - mu) * rs); pw.y = cvt_pk_bf16((acc[q][4 * g4 + 2] - mu) * rs, (acc[q][4 * g4 + 3] - mu) * rs);
;             *(LAS u32x2*)(Ol + n * OL_STRIDE + 32 * w + 8 * g4 + 4 * hh) = pw; } }
;     __syncthreads();
; #pragma unroll
;     for (int it = 0; it < 8; ++it) { const int id = tid + NTHREADS * it, tq = id >> 5, d8 = (id & 31) * 8;
;         float y[8], rg[8], o[8]; unpack8(*(const LAS u32x4*)(Ol + tq * OL_STRIDE + d8), y);
;         unpack8(__builtin_nontemporal_load((const u32x4*)(proj + (size_t)(tok0 + tq) * NPROJ + 2048 + h * 256 + d8)), rg);
;         const f32x4 g0 = *(const f32x4*)(gn + h * 256 + d8), g1 = *(const f32x4*)(gn + h * 256 + d8 + 4);
; #pragma unroll
;         for (int j = 0; j < 8; ++j) { const float gv = j < 4 ? g0[j & 3] : g1[j & 3]; o[j] = rg[j] * sigmoidf_(rg[j]) * y[j] * gv; }
;         *(u32x4*)(ro + (size_t)(tok0 + tq) * 1536 + 512 + h * 256 + d8) = pack8(o); }
	v_pk_add_f32 v[18:19], v[22:23], v[18:19]
	s_nop 0
	v_pk_add_f32 v[18:19], v[18:19], v[20:21]
	v_mov_b64_e32 v[22:23], s[40:41]
	v_pk_mul_f32 v[18:19], v[18:19], s[66:67] op_sel_hi:[1,0]
	s_nop 0
	v_fma_f32 v0, -v18, v18, v19
	v_cmp_ngt_f32_e32 vcc, 0, v0
	v_pk_add_f32 v[2:3], v[2:3], v[18:19] op_sel_hi:[1,0] neg_lo:[0,1] neg_hi:[0,1]
	v_pk_add_f32 v[4:5], v[4:5], v[18:19] op_sel_hi:[1,0] neg_lo:[0,1] neg_hi:[0,1]
	v_cndmask_b32_e32 v0, 0, v0, vcc
	v_add_f32_e32 v0, 0x358637bd, v0
	v_cmp_gt_f32_e32 vcc, s65, v0
	v_mul_f32_e32 v20, 0x4b800000, v0
	s_nop 0
	v_cndmask_b32_e32 v0, v0, v20, vcc
	v_rsq_f32_e32 v0, v0
	s_nop 0
	v_mul_f32_e32 v20, 0x45800000, v0
	v_cndmask_b32_e32 v0, v0, v20, vcc
	v_pk_mul_f32 v[2:3], v[2:3], v[0:1] op_sel_hi:[1,0]
	v_pk_mul_f32 v[4:5], v[4:5], v[0:1] op_sel_hi:[1,0]
	v_cvt_pk_bf16_f32 v2, v2, v3
	v_cvt_pk_bf16_f32 v3, v4, v5
	v_pk_add_f32 v[4:5], v[6:7], v[18:19] op_sel_hi:[1,0] neg_lo:[0,1] neg_hi:[0,1]
	v_pk_add_f32 v[6:7], v[8:9], v[18:19] op_sel_hi:[1,0] neg_lo:[0,1] neg_hi:[0,1]
	v_pk_mul_f32 v[4:5], v[4:5], v[0:1] op_sel_hi:[1,0]
	v_pk_mul_f32 v[6:7], v[6:7], v[0:1] op_sel_hi:[1,0]
	v_cvt_pk_bf16_f32 v4, v4, v5
	v_cvt_pk_bf16_f32 v5, v6, v7
	v_add_u32_e32 v8, 0xc000, v68
	ds_write2_b64 v8, v[2:3], v[4:5] offset0:192 offset1:194
	v_pk_add_f32 v[2:3], v[10:11], v[18:19] op_sel_hi:[1,0] neg_lo:[0,1] neg_hi:[0,1]
	v_pk_add_f32 v[4:5], v[12:13], v[18:19] op_sel_hi:[1,0] neg_lo:[0,1] neg_hi:[0,1]
	v_pk_mul_f32 v[2:3], v[2:3], v[0:1] op_sel_hi:[1,0]
	v_pk_mul_f32 v[4:5], v[4:5], v[0:1] op_sel_hi:[1,0]
	v_cvt_pk_bf16_f32 v2, v2, v3
	v_cvt_pk_bf16_f32 v3, v4, v5
	v_pk_add_f32 v[4:5], v[14:15], v[18:19] op_sel_hi:[1,0] neg_lo:[0,1] neg_hi:[0,1]
	v_pk_add_f32 v[6:7], v[16:17], v[18:19] op_sel_hi:[1,0] neg_lo:[0,1] neg_hi:[0,1]
	v_pk_mul_f32 v[4:5], v[4:5], v[0:1] op_sel_hi:[1,0]
	v_pk_mul_f32 v[6:7], v[6:7], v[0:1] op_sel_hi:[1,0]
	v_cvt_pk_bf16_f32 v4, v4, v5
	v_cvt_pk_bf16_f32 v5, v6, v7
	ds_write2_b64 v8, v[2:3], v[4:5] offset0:196 offset1:198
	v_and_b32_e32 v2, 0xf8, v249
	v_lshlrev_b32_e32 v0, 1, v2
	v_add_u32_e32 v20, 0, v0
	v_lshlrev_b32_e32 v6, 2, v2
	v_ashrrev_i32_e32 v14, 5, v247
	s_waitcnt lgkmcnt(0)
	s_barrier
	s_waitcnt vmcnt(0)
	v_mov_b64 v[2:3], v[112:113]
	v_mov_b64 v[4:5], v[114:115]
	s_nop 0
	v_mov_b64 v[6:7], v[116:117]
	v_mov_b64 v[8:9], v[118:119]
	v_mad_u64_u32 v[10:11], s[10:11], v14, s56, v[20:21]
	v_add_u32_e32 v21, s6, v14
	v_mad_i64_i32 v[14:15], s[10:11], v21, s18, v[22:23]
	v_lshl_add_u64 v[14:15], v[14:15], 0, s[58:59]
	v_lshl_add_u64 v[14:15], v[14:15], 0, v[0:1]
	v_add_co_u32_e32 v14, vcc, s23, v14
	ds_read_b128 v[10:13], v10
	s_nop 0
	v_addc_co_u32_e32 v15, vcc, 0, v15, vcc
	s_waitcnt vmcnt(0)
	v_mov_b64_e32 v[14:15], v[80:81]
	v_mov_b64_e32 v[16:17], v[82:83]
	s_waitcnt lgkmcnt(0)
	v_lshlrev_b32_e32 v18, 16, v10
	v_and_b32_e32 v19, 0xffff0000, v10
	s_waitcnt vmcnt(0)
	v_lshlrev_b32_e32 v24, 16, v14
	v_mul_f32_e32 v10, 0xbfb8aa3b, v24
	v_exp_f32_e32 v10, v10
	v_and_b32_e32 v25, 0xffff0000, v14
	v_lshlrev_b32_e32 v14, 16, v15
	v_and_b32_e32 v15, 0xffff0000, v15
	v_add_f32_e32 v10, 1.0, v10
	v_rcp_f32_e32 v26, v10
	v_mul_f32_e32 v10, 0xbfb8aa3b, v25
	v_exp_f32_e32 v10, v10
	s_nop 0
	v_add_f32_e32 v10, 1.0, v10
	v_rcp_f32_e32 v27, v10
	v_lshlrev_b32_e32 v10, 16, v11
	v_and_b32_e32 v11, 0xffff0000, v11
	v_pk_mul_f32 v[24:25], v[26:27], v[24:25]
	s_nop 0
	v_pk_mul_f32 v[18:19], v[24:25], v[18:19]
	v_mul_f32_e32 v24, 0xbfb8aa3b, v14
	v_mul_f32_e32 v25, 0xbfb8aa3b, v15
	v_exp_f32_e32 v24, v24
	v_exp_f32_e32 v25, v25
	v_pk_mul_f32 v[18:19], v[6:7], v[18:19]
	v_add_f32_e32 v24, 1.0, v24
	v_add_f32_e32 v25, 1.0, v25
	v_rcp_f32_e32 v24, v24
	v_rcp_f32_e32 v25, v25
	s_nop 0
	v_pk_mul_f32 v[14:15], v[24:25], v[14:15]
	s_nop 0
	v_pk_mul_f32 v[10:11], v[14:15], v[10:11]
	v_lshlrev_b32_e32 v24, 16, v16
	v_pk_mul_f32 v[14:15], v[8:9], v[10:11]
	v_lshlrev_b32_e32 v10, 16, v12
	v_and_b32_e32 v11, 0xffff0000, v12
	v_mul_f32_e32 v12, 0xbfb8aa3b, v24
	v_exp_f32_e32 v12, v12
	v_and_b32_e32 v25, 0xffff0000, v16
	v_add_f32_e32 v12, 1.0, v12
	v_rcp_f32_e32 v26, v12
	v_mul_f32_e32 v12, 0xbfb8aa3b, v25
	v_exp_f32_e32 v12, v12
	s_nop 0
	v_add_f32_e32 v12, 1.0, v12
	v_rcp_f32_e32 v27, v12
	v_lshlrev_b32_e32 v12, 16, v17
	v_mul_f32_e32 v16, 0xbfb8aa3b, v12
	v_exp_f32_e32 v16, v16
	v_pk_mul_f32 v[24:25], v[26:27], v[24:25]
	v_add_f32_e32 v16, 1.0, v16
	v_pk_mul_f32 v[10:11], v[24:25], v[10:11]
	v_rcp_f32_e32 v16, v16
	v_pk_mul_f32 v[24:25], v[2:3], v[10:11]
	v_lshlrev_b32_e32 v10, 16, v13
	v_and_b32_e32 v11, 0xffff0000, v13
	v_and_b32_e32 v13, 0xffff0000, v17
	v_mul_f32_e32 v17, 0xbfb8aa3b, v13
	v_exp_f32_e32 v17, v17
	s_nop 0
	v_add_f32_e32 v17, 1.0, v17
	v_rcp_f32_e32 v17, v17
	s_nop 0
	v_pk_mul_f32 v[12:13], v[16:17], v[12:13]
	s_nop 0
	v_pk_mul_f32 v[10:11], v[12:13], v[10:11]
	v_cvt_pk_bf16_f32 v12, v24, v25
	v_pk_mul_f32 v[16:17], v[4:5], v[10:11]
	v_cvt_pk_bf16_f32 v10, v18, v19
	v_mov_b64_e32 v[18:19], s[4:5]
	v_cvt_pk_bf16_f32 v11, v14, v15
	v_mad_i64_i32 v[14:15], s[4:5], v21, s24, v[18:19]
	v_lshl_add_u64 v[14:15], v[14:15], 0, s[58:59]
	v_cvt_pk_bf16_f32 v13, v16, v17
	v_lshl_add_u64 v[14:15], v[14:15], 0, v[0:1]
	global_store_dwordx4 v[14:15], v[10:13], off offset:1024
	v_ashrrev_i32_e32 v14, 5, v248
	s_nop 0
	v_mad_u64_u32 v[10:11], s[4:5], v14, s56, v[20:21]
	v_add_u32_e32 v21, s6, v14
	v_mad_i64_i32 v[14:15], s[4:5], v21, s18, v[22:23]
	v_lshl_add_u64 v[14:15], v[14:15], 0, s[58:59]
	v_lshl_add_u64 v[14:15], v[14:15], 0, v[0:1]
	v_add_co_u32_e32 v14, vcc, s23, v14
	ds_read_b128 v[10:13], v10
	s_nop 0
	v_addc_co_u32_e32 v15, vcc, 0, v15, vcc
	v_mov_b64_e32 v[14:15], v[84:85]
	v_mov_b64_e32 v[16:17], v[86:87]
	s_waitcnt lgkmcnt(0)
; #define LAS __attribute__((address_space(3)))
; __device__ __forceinline__ float sigmoidf_(float x) { return __builtin_amdgcn_rcpf(1.0f + __expf(-x)); }
; __device__ __forceinline__ void unpack8(const u32x4 w, float* f) { f[0] = bf_lo(w.x); f[1] = bf_hi(w.x); f[2] = bf_lo(w.y); f[3] = bf_hi(w.y); f[4] = bf_lo(w.z); f[5] = bf_hi(w.z); f[6] = bf_lo(w.w); f[7] = bf_hi(w.w); }
; __device__ __forceinline__ u32x4 pack8(const float* f) { u32x4 w; w.x = cvt_pk_bf16(f[0], f[1]); w.y = cvt_pk_bf16(f[2], f[3]); w.z = cvt_pk_bf16(f[4], f[5]); w.w = cvt_pk_bf16(f[6], f[7]); return w; }
; __device__ __forceinline__ void r3_item(const bf16_t* __restrict__ proj, const bf16_t* __restrict__ projT, const bf16_t* __restrict__ st, bf16_t* ro, ...
;     ...
; #pragma unroll
;     for (int it = 0; it < 8; ++it) { const int id = tid + NTHREADS * it, tq = id >> 5, d8 = (id & 31) * 8;
;         float y[8], rg[8], o[8]; unpack8(*(const LAS u32x4*)(Ol + tq * OL_STRIDE + d8), y);
;         unpack8(__builtin_nontemporal_load((const u32x4*)(proj + (size_t)(tok0 + tq) * NPROJ + 2048 + h * 256 + d8)), rg);
;         const f32x4 g0 = *(const f32x4*)(gn + h * 256 + d8), g1 = *(const f32x4*)(gn + h * 256 + d8 + 4);
; #pragma unroll
;         for (int j = 0; j < 8; ++j) { const float gv = j < 4 ? g0[j & 3] : g1[j & 3]; o[j] = rg[j] * sigmoidf_(rg[j]) * y[j] * gv; }
;         *(u32x4*)(ro + (size_t)(tok0 + tq) * 1536 + 512 + h * 256 + d8) = pack8(o); }
	v_lshlrev_b32_e32 v24, 16, v10
	v_and_b32_e32 v25, 0xffff0000, v10
	v_lshlrev_b32_e32 v26, 16, v14
	v_mul_f32_e32 v10, 0xbfb8aa3b, v26
	v_exp_f32_e32 v10, v10
	v_and_b32_e32 v27, 0xffff0000, v14
	v_lshlrev_b32_e32 v14, 16, v15
	v_and_b32_e32 v15, 0xffff0000, v15
	v_add_f32_e32 v10, 1.0, v10
	v_rcp_f32_e32 v28, v10
	v_mul_f32_e32 v10, 0xbfb8aa3b, v27
	v_exp_f32_e32 v10, v10
	s_nop 0
	v_add_f32_e32 v10, 1.0, v10
	v_rcp_f32_e32 v29, v10
	v_lshlrev_b32_e32 v10, 16, v11
	v_and_b32_e32 v11, 0xffff0000, v11
	v_pk_mul_f32 v[26:27], v[28:29], v[26:27]
	s_nop 0
	v_pk_mul_f32 v[24:25], v[26:27], v[24:25]
	v_mul_f32_e32 v26, 0xbfb8aa3b, v14
	v_mul_f32_e32 v27, 0xbfb8aa3b, v15
	v_exp_f32_e32 v26, v26
	v_exp_f32_e32 v27, v27
	v_pk_mul_f32 v[24:25], v[6:7], v[24:25]
	v_add_f32_e32 v26, 1.0, v26
	v_add_f32_e32 v27, 1.0, v27
	v_rcp_f32_e32 v26, v26
	v_rcp_f32_e32 v27, v27
	s_nop 0
	v_pk_mul_f32 v[14:15], v[26:27], v[14:15]
	s_nop 0
	v_pk_mul_f32 v[10:11], v[14:15], v[10:11]
	v_lshlrev_b32_e32 v26, 16, v16
	v_pk_mul_f32 v[14:15], v[8:9], v[10:11]
	v_lshlrev_b32_e32 v10, 16, v12
	v_and_b32_e32 v11, 0xffff0000, v12
	v_mul_f32_e32 v12, 0xbfb8aa3b, v26
	v_exp_f32_e32 v12, v12
	v_and_b32_e32 v27, 0xffff0000, v16
	v_add_f32_e32 v12, 1.0, v12
	v_rcp_f32_e32 v28, v12
	v_mul_f32_e32 v12, 0xbfb8aa3b, v27
	v_exp_f32_e32 v12, v12
	s_nop 0
	v_add_f32_e32 v12, 1.0, v12
	v_rcp_f32_e32 v29, v12
	v_lshlrev_b32_e32 v12, 16, v17
	v_mul_f32_e32 v16, 0xbfb8aa3b, v12
	v_exp_f32_e32 v16, v16
	v_pk_mul_f32 v[26:27], v[28:29], v[26:27]
	v_add_f32_e32 v16, 1.0, v16
	v_pk_mul_f32 v[10:11], v[26:27], v[10:11]
	v_rcp_f32_e32 v16, v16
	v_pk_mul_f32 v[26:27], v[2:3], v[10:11]
	v_lshlrev_b32_e32 v10, 16, v13
	v_and_b32_e32 v11, 0xffff0000, v13
	v_and_b32_e32 v13, 0xffff0000, v17
	v_mul_f32_e32 v17, 0xbfb8aa3b, v13
	v_exp_f32_e32 v17, v17
	s_nop 0
	v_add_f32_e32 v17, 1.0, v17
	v_rcp_f32_e32 v17, v17
	s_nop 0
	v_pk_mul_f32 v[12:13], v[16:17], v[12:13]
	s_nop 0
	v_pk_mul_f32 v[10:11], v[12:13], v[10:11]
	v_cvt_pk_bf16_f32 v12, v26, v27
	v_pk_mul_f32 v[16:17], v[4:5], v[10:11]
	v_cvt_pk_bf16_f32 v11, v14, v15
	v_mad_i64_i32 v[14:15], s[4:5], v21, s24, v[18:19]
	v_lshl_add_u64 v[14:15], v[14:15], 0, s[58:59]
	v_cvt_pk_bf16_f32 v10, v24, v25
	v_cvt_pk_bf16_f32 v13, v16, v17
	v_lshl_add_u64 v[14:15], v[14:15], 0, v[0:1]
	global_store_dwordx4 v[14:15], v[10:13], off offset:1024
	s_nop 1
	v_add_u32_e32 v10, 0x400, v247
	v_ashrrev_i32_e32 v14, 5, v10
	v_mad_u64_u32 v[10:11], s[4:5], v14, s56, v[20:21]
	v_add_u32_e32 v21, s6, v14
	v_mad_i64_i32 v[14:15], s[4:5], v21, s18, v[22:23]
	v_lshl_add_u64 v[14:15], v[14:15], 0, s[58:59]
	v_lshl_add_u64 v[14:15], v[14:15], 0, v[0:1]
	v_add_co_u32_e32 v14, vcc, s23, v14
	ds_read_b128 v[10:13], v10
	s_nop 0
	v_addc_co_u32_e32 v15, vcc, 0, v15, vcc
	v_mov_b64_e32 v[14:15], v[88:89]
	v_mov_b64_e32 v[16:17], v[90:91]
	s_waitcnt lgkmcnt(0)
	v_lshlrev_b32_e32 v24, 16, v10
	v_and_b32_e32 v25, 0xffff0000, v10
	v_lshlrev_b32_e32 v26, 16, v14
	v_mul_f32_e32 v10, 0xbfb8aa3b, v26
	v_exp_f32_e32 v10, v10
	v_and_b32_e32 v27, 0xffff0000, v14
	v_lshlrev_b32_e32 v14, 16, v15
	v_and_b32_e32 v15, 0xffff0000, v15
	v_add_f32_e32 v10, 1.0, v10
	v_rcp_f32_e32 v28, v10
	v_mul_f32_e32 v10, 0xbfb8aa3b, v27
	v_exp_f32_e32 v10, v10
	s_nop 0
	v_add_f32_e32 v10, 1.0, v10
	v_rcp_f32_e32 v29, v10
	v_lshlrev_b32_e32 v10, 16, v11
	v_and_b32_e32 v11, 0xffff0000, v11
	v_pk_mul_f32 v[26:27], v[28:29], v[26:27]
	s_nop 0
	v_pk_mul_f32 v[24:25], v[26:27], v[24:25]
	v_mul_f32_e32 v26, 0xbfb8aa3b, v14
	v_mul_f32_e32 v27, 0xbfb8aa3b, v15
	v_exp_f32_e32 v26, v26
	v_exp_f32_e32 v27, v27
	v_pk_mul_f32 v[24:25], v[6:7], v[24:25]
	v_add_f32_e32 v26, 1.0, v26
	v_add_f32_e32 v27, 1.0, v27
	v_rcp_f32_e32 v26, v26
	v_rcp_f32_e32 v27, v27
	s_nop 0
	v_pk_mul_f32 v[14:15], v[26:27], v[14:15]
	s_nop 0
	v_pk_mul_f32 v[10:11], v[14:15], v[10:11]
	v_lshlrev_b32_e32 v26, 16, v16
	v_pk_mul_f32 v[14:15], v[8:9], v[10:11]
	v_lshlrev_b32_e32 v10, 16, v12
	v_and_b32_e32 v11, 0xffff0000, v12
	v_mul_f32_e32 v12, 0xbfb8aa3b, v26
	v_exp_f32_e32 v12, v12
	v_and_b32_e32 v27, 0xffff0000, v16
	v_add_f32_e32 v12, 1.0, v12
	v_rcp_f32_e32 v28, v12
	v_mul_f32_e32 v12, 0xbfb8aa3b, v27
	v_exp_f32_e32 v12, v12
	s_nop 0
	v_add_f32_e32 v12, 1.0, v12
	v_rcp_f32_e32 v29, v12
	v_lshlrev_b32_e32 v12, 16, v17
	v_mul_f32_e32 v16, 0xbfb8aa3b, v12
	v_exp_f32_e32 v16, v16
	v_pk_mul_f32 v[26:27], v[28:29], v[26:27]
	v_add_f32_e32 v16, 1.0, v16
	v_pk_mul_f32 v[10:11], v[26:27], v[10:11]
	v_rcp_f32_e32 v16, v16
	v_pk_mul_f32 v[26:27], v[2:3], v[10:11]
	v_lshlrev_b32_e32 v10, 16, v13
	v_and_b32_e32 v11, 0xffff0000, v13
	v_and_b32_e32 v13, 0xffff0000, v17
	v_mul_f32_e32 v17, 0xbfb8aa3b, v13
	v_exp_f32_e32 v17, v17
	s_nop 0
	v_add_f32_e32 v17, 1.0, v17
	v_rcp_f32_e32 v17, v17
	s_nop 0
	v_pk_mul_f32 v[12:13], v[16:17], v[12:13]
	s_nop 0
	v_pk_mul_f32 v[10:11], v[12:13], v[10:11]
	v_cvt_pk_bf16_f32 v12, v26, v27
	v_pk_mul_f32 v[16:17], v[4:5], v[10:11]
	v_cvt_pk_bf16_f32 v11, v14, v15
	v_mad_i64_i32 v[14:15], s[4:5], v21, s24, v[18:19]
	v_lshl_add_u64 v[14:15], v[14:15], 0, s[58:59]
	v_cvt_pk_bf16_f32 v10, v24, v25
	v_cvt_pk_bf16_f32 v13, v16, v17
	v_lshl_add_u64 v[14:15], v[14:15], 0, v[0:1]
	global_store_dwordx4 v[14:15], v[10:13], off offset:1024
	s_nop 1
	v_add_u32_e32 v10, 0x600, v247
	v_ashrrev_i32_e32 v14, 5, v10
	v_mad_u64_u32 v[10:11], s[4:5], v14, s56, v[20:21]
	v_add_u32_e32 v21, s6, v14
	v_mad_i64_i32 v[14:15], s[4:5], v21, s18, v[22:23]
	v_lshl_add_u64 v[14:15], v[14:15], 0, s[58:59]
	v_lshl_add_u64 v[14:15], v[14:15], 0, v[0:1]
	v_add_co_u32_e32 v14, vcc, s23, v14
	ds_read_b128 v[10:13], v10
	s_nop 0
	v_addc_co_u32_e32 v15, vcc, 0, v15, vcc
	v_mov_b64_e32 v[14:15], v[92:93]
	v_mov_b64_e32 v[16:17], v[94:95]
	s_waitcnt lgkmcnt(0)
; #define LAS __attribute__((address_space(3)))
; __device__ __forceinline__ float sigmoidf_(float x) { return __builtin_amdgcn_rcpf(1.0f + __expf(-x)); }
; __device__ __forceinline__ void unpack8(const u32x4 w, float* f) { f[0] = bf_lo(w.x); f[1] = bf_hi(w.x); f[2] = bf_lo(w.y); f[3] = bf_hi(w.y); f[4] = bf_lo(w.z); f[5] = bf_hi(w.z); f[6] = bf_lo(w.w); f[7] = bf_hi(w.w); }
; __device__ __forceinline__ u32x4 pack8(const float* f) { u32x4 w; w.x = cvt_pk_bf16(f[0], f[1]); w.y = cvt_pk_bf16(f[2], f[3]); w.z = cvt_pk_bf16(f[4], f[5]); w.w = cvt_pk_bf16(f[6], f[7]); return w; }
; __device__ __forceinline__ void r3_item(const bf16_t* __restrict__ proj, const bf16_t* __restrict__ projT, const bf16_t* __restrict__ st, bf16_t* ro, ...
;     ...
; #pragma unroll
;     for (int it = 0; it < 8; ++it) { const int id = tid + NTHREADS * it, tq = id >> 5, d8 = (id & 31) * 8;
;         float y[8], rg[8], o[8]; unpack8(*(const LAS u32x4*)(Ol + tq * OL_STRIDE + d8), y);
;         unpack8(__builtin_nontemporal_load((const u32x4*)(proj + (size_t)(tok0 + tq) * NPROJ + 2048 + h * 256 + d8)), rg);
;         const f32x4 g0 = *(const f32x4*)(gn + h * 256 + d8), g1 = *(const f32x4*)(gn + h * 256 + d8 + 4);
; #pragma unroll
;         for (int j = 0; j < 8; ++j) { const float gv = j < 4 ? g0[j & 3] : g1[j & 3]; o[j] = rg[j] * sigmoidf_(rg[j]) * y[j] * gv; }
;         *(u32x4*)(ro + (size_t)(tok0 + tq) * 1536 + 512 + h * 256 + d8) = pack8(o); }
	v_lshlrev_b32_e32 v24, 16, v10
	v_and_b32_e32 v25, 0xffff0000, v10
	v_lshlrev_b32_e32 v26, 16, v14
	v_mul_f32_e32 v10, 0xbfb8aa3b, v26
	v_exp_f32_e32 v10, v10
	v_and_b32_e32 v27, 0xffff0000, v14
	v_lshlrev_b32_e32 v14, 16, v15
	v_and_b32_e32 v15, 0xffff0000, v15
	v_add_f32_e32 v10, 1.0, v10
	v_rcp_f32_e32 v28, v10
	v_mul_f32_e32 v10, 0xbfb8aa3b, v27
	v_exp_f32_e32 v10, v10
	s_nop 0
	v_add_f32_e32 v10, 1.0, v10
	v_rcp_f32_e32 v29, v10
	v_lshlrev_b32_e32 v10, 16, v11
	v_and_b32_e32 v11, 0xffff0000, v11
	v_pk_mul_f32 v[26:27], v[28:29], v[26:27]
	s_nop 0
	v_pk_mul_f32 v[24:25], v[26:27], v[24:25]
	v_mul_f32_e32 v26, 0xbfb8aa3b, v14
	v_mul_f32_e32 v27, 0xbfb8aa3b, v15
	v_exp_f32_e32 v26, v26
	v_exp_f32_e32 v27, v27
	v_pk_mul_f32 v[24:25], v[6:7], v[24:25]
	v_add_f32_e32 v26, 1.0, v26
	v_add_f32_e32 v27, 1.0, v27
	v_rcp_f32_e32 v26, v26
	v_rcp_f32_e32 v27, v27
	s_nop 0
	v_pk_mul_f32 v[14:15], v[26:27], v[14:15]
	s_nop 0
	v_pk_mul_f32 v[10:11], v[14:15], v[10:11]
	v_lshlrev_b32_e32 v26, 16, v16
	v_pk_mul_f32 v[14:15], v[8:9], v[10:11]
	v_lshlrev_b32_e32 v10, 16, v12
	v_and_b32_e32 v11, 0xffff0000, v12
	v_mul_f32_e32 v12, 0xbfb8aa3b, v26
	v_exp_f32_e32 v12, v12
	v_and_b32_e32 v27, 0xffff0000, v16
	v_add_f32_e32 v12, 1.0, v12
	v_rcp_f32_e32 v28, v12
	v_mul_f32_e32 v12, 0xbfb8aa3b, v27
	v_exp_f32_e32 v12, v12
	s_nop 0
	v_add_f32_e32 v12, 1.0, v12
	v_rcp_f32_e32 v29, v12
	v_lshlrev_b32_e32 v12, 16, v17
	v_mul_f32_e32 v16, 0xbfb8aa3b, v12
	v_exp_f32_e32 v16, v16
	v_pk_mul_f32 v[26:27], v[28:29], v[26:27]
	v_add_f32_e32 v16, 1.0, v16
	v_pk_mul_f32 v[10:11], v[26:27], v[10:11]
	v_rcp_f32_e32 v16, v16
	v_pk_mul_f32 v[26:27], v[2:3], v[10:11]
	v_lshlrev_b32_e32 v10, 16, v13
	v_and_b32_e32 v11, 0xffff0000, v13
	v_and_b32_e32 v13, 0xffff0000, v17
	v_mul_f32_e32 v17, 0xbfb8aa3b, v13
	v_exp_f32_e32 v17, v17
	s_nop 0
	v_add_f32_e32 v17, 1.0, v17
	v_rcp_f32_e32 v17, v17
	s_nop 0
	v_pk_mul_f32 v[12:13], v[16:17], v[12:13]
	s_nop 0
	v_pk_mul_f32 v[10:11], v[12:13], v[10:11]
	v_cvt_pk_bf16_f32 v12, v26, v27
	v_pk_mul_f32 v[16:17], v[4:5], v[10:11]
	v_cvt_pk_bf16_f32 v11, v14, v15
	v_mad_i64_i32 v[14:15], s[4:5], v21, s24, v[18:19]
	v_lshl_add_u64 v[14:15], v[14:15], 0, s[58:59]
	v_cvt_pk_bf16_f32 v10, v24, v25
	v_cvt_pk_bf16_f32 v13, v16, v17
	v_lshl_add_u64 v[14:15], v[14:15], 0, v[0:1]
	global_store_dwordx4 v[14:15], v[10:13], off offset:1024
	s_nop 1
	v_add_u32_e32 v10, 0x800, v247
	v_ashrrev_i32_e32 v14, 5, v10
	v_mad_u64_u32 v[10:11], s[4:5], v14, s56, v[20:21]
	v_add_u32_e32 v21, s6, v14
	v_mad_i64_i32 v[14:15], s[4:5], v21, s18, v[22:23]
	v_lshl_add_u64 v[14:15], v[14:15], 0, s[58:59]
	v_lshl_add_u64 v[14:15], v[14:15], 0, v[0:1]
	v_add_co_u32_e32 v14, vcc, s23, v14
	ds_read_b128 v[10:13], v10
	s_nop 0
	v_addc_co_u32_e32 v15, vcc, 0, v15, vcc
	v_mov_b64_e32 v[14:15], v[96:97]
	v_mov_b64_e32 v[16:17], v[98:99]
	s_waitcnt lgkmcnt(0)
	v_lshlrev_b32_e32 v24, 16, v10
	v_and_b32_e32 v25, 0xffff0000, v10
	v_lshlrev_b32_e32 v26, 16, v14
	v_mul_f32_e32 v10, 0xbfb8aa3b, v26
	v_exp_f32_e32 v10, v10
	v_and_b32_e32 v27, 0xffff0000, v14
	v_lshlrev_b32_e32 v14, 16, v15
	v_and_b32_e32 v15, 0xffff0000, v15
	v_add_f32_e32 v10, 1.0, v10
	v_rcp_f32_e32 v28, v10
	v_mul_f32_e32 v10, 0xbfb8aa3b, v27
	v_exp_f32_e32 v10, v10
	s_nop 0
	v_add_f32_e32 v10, 1.0, v10
	v_rcp_f32_e32 v29, v10
	v_lshlrev_b32_e32 v10, 16, v11
	v_and_b32_e32 v11, 0xffff0000, v11
	v_pk_mul_f32 v[26:27], v[28:29], v[26:27]
	s_nop 0
	v_pk_mul_f32 v[24:25], v[26:27], v[24:25]
	v_mul_f32_e32 v26, 0xbfb8aa3b, v14
	v_mul_f32_e32 v27, 0xbfb8aa3b, v15
	v_exp_f32_e32 v26, v26
	v_exp_f32_e32 v27, v27
	v_pk_mul_f32 v[24:25], v[6:7], v[24:25]
	v_add_f32_e32 v26, 1.0, v26
	v_add_f32_e32 v27, 1.0, v27
	v_rcp_f32_e32 v26, v26
	v_rcp_f32_e32 v27, v27
	s_nop 0
	v_pk_mul_f32 v[14:15], v[26:27], v[14:15]
	s_nop 0
	v_pk_mul_f32 v[10:11], v[14:15], v[10:11]
	v_lshlrev_b32_e32 v26, 16, v16
	v_pk_mul_f32 v[14:15], v[8:9], v[10:11]
	v_lshlrev_b32_e32 v10, 16, v12
	v_and_b32_e32 v11, 0xffff0000, v12
	v_mul_f32_e32 v12, 0xbfb8aa3b, v26
	v_exp_f32_e32 v12, v12
	v_and_b32_e32 v27, 0xffff0000, v16
	v_add_f32_e32 v12, 1.0, v12
	v_rcp_f32_e32 v28, v12
	v_mul_f32_e32 v12, 0xbfb8aa3b, v27
	v_exp_f32_e32 v12, v12
	s_nop 0
	v_add_f32_e32 v12, 1.0, v12
	v_rcp_f32_e32 v29, v12
	v_lshlrev_b32_e32 v12, 16, v17
	v_mul_f32_e32 v16, 0xbfb8aa3b, v12
	v_exp_f32_e32 v16, v16
	v_pk_mul_f32 v[26:27], v[28:29], v[26:27]
	v_add_f32_e32 v16, 1.0, v16
	v_pk_mul_f32 v[10:11], v[26:27], v[10:11]
	v_rcp_f32_e32 v16, v16
	v_pk_mul_f32 v[26:27], v[2:3], v[10:11]
	v_lshlrev_b32_e32 v10, 16, v13
	v_and_b32_e32 v11, 0xffff0000, v13
	v_and_b32_e32 v13, 0xffff0000, v17
	v_mul_f32_e32 v17, 0xbfb8aa3b, v13
	v_exp_f32_e32 v17, v17
	s_nop 0
	v_add_f32_e32 v17, 1.0, v17
	v_rcp_f32_e32 v17, v17
	s_nop 0
	v_pk_mul_f32 v[12:13], v[16:17], v[12:13]
	s_nop 0
	v_pk_mul_f32 v[10:11], v[12:13], v[10:11]
	v_cvt_pk_bf16_f32 v12, v26, v27
	v_pk_mul_f32 v[16:17], v[4:5], v[10:11]
	v_cvt_pk_bf16_f32 v11, v14, v15
	v_mad_i64_i32 v[14:15], s[4:5], v21, s24, v[18:19]
	v_lshl_add_u64 v[14:15], v[14:15], 0, s[58:59]
	v_cvt_pk_bf16_f32 v10, v24, v25
	v_cvt_pk_bf16_f32 v13, v16, v17
	v_lshl_add_u64 v[14:15], v[14:15], 0, v[0:1]
	global_store_dwordx4 v[14:15], v[10:13], off offset:1024
	s_nop 1
	v_add_u32_e32 v10, 0xa00, v247
	v_ashrrev_i32_e32 v14, 5, v10
	v_mad_u64_u32 v[10:11], s[4:5], v14, s56, v[20:21]
	v_add_u32_e32 v21, s6, v14
	v_mad_i64_i32 v[14:15], s[4:5], v21, s18, v[22:23]
	v_lshl_add_u64 v[14:15], v[14:15], 0, s[58:59]
	v_lshl_add_u64 v[14:15], v[14:15], 0, v[0:1]
	v_add_co_u32_e32 v14, vcc, s23, v14
	ds_read_b128 v[10:13], v10
	s_nop 0
	v_addc_co_u32_e32 v15, vcc, 0, v15, vcc
	v_mov_b64_e32 v[14:15], v[100:101]
	v_mov_b64_e32 v[16:17], v[102:103]
	s_waitcnt lgkmcnt(0)
; #define LAS __attribute__((address_space(3)))
; __device__ __forceinline__ float sigmoidf_(float x) { return __builtin_amdgcn_rcpf(1.0f + __expf(-x)); }
; __device__ __forceinline__ void unpack8(const u32x4 w, float* f) { f[0] = bf_lo(w.x); f[1] = bf_hi(w.x); f[2] = bf_lo(w.y); f[3] = bf_hi(w.y); f[4] = bf_lo(w.z); f[5] = bf_hi(w.z); f[6] = bf_lo(w.w); f[7] = bf_hi(w.w); }
; __device__ __forceinline__ u32x4 pack8(const float* f) { u32x4 w; w.x = cvt_pk_bf16(f[0], f[1]); w.y = cvt_pk_bf16(f[2], f[3]); w.z = cvt_pk_bf16(f[4], f[5]); w.w = cvt_pk_bf16(f[6], f[7]); return w; }
; __device__ __forceinline__ void r3_item(const bf16_t* __restrict__ proj, const bf16_t* __restrict__ projT, const bf16_t* __restrict__ st, bf16_t* ro, ...
;     ...
; #pragma unroll
;     for (int it = 0; it < 8; ++it) { const int id = tid + NTHREADS * it, tq = id >> 5, d8 = (id & 31) * 8;
;         float y[8], rg[8], o[8]; unpack8(*(const LAS u32x4*)(Ol + tq * OL_STRIDE + d8), y);
;         unpack8(__builtin_nontemporal_load((const u32x4*)(proj + (size_t)(tok0 + tq) * NPROJ + 2048 + h * 256 + d8)), rg);
;         const f32x4 g0 = *(const f32x4*)(gn + h * 256 + d8), g1 = *(const f32x4*)(gn + h * 256 + d8 + 4);
; #pragma unroll
;         for (int j = 0; j < 8; ++j) { const float gv = j < 4 ? g0[j & 3] : g1[j & 3]; o[j] = rg[j] * sigmoidf_(rg[j]) * y[j] * gv; }
;         *(u32x4*)(ro + (size_t)(tok0 + tq) * 1536 + 512 + h * 256 + d8) = pack8(o); }
	v_lshlrev_b32_e32 v24, 16, v10
	v_and_b32_e32 v25, 0xffff0000, v10
	v_lshlrev_b32_e32 v26, 16, v14
	v_mul_f32_e32 v10, 0xbfb8aa3b, v26
	v_exp_f32_e32 v10, v10
	v_and_b32_e32 v27, 0xffff0000, v14
	v_lshlrev_b32_e32 v14, 16, v15
	v_and_b32_e32 v15, 0xffff0000, v15
	v_add_f32_e32 v10, 1.0, v10
	v_rcp_f32_e32 v28, v10
	v_mul_f32_e32 v10, 0xbfb8aa3b, v27
	v_exp_f32_e32 v10, v10
	s_nop 0
	v_add_f32_e32 v10, 1.0, v10
	v_rcp_f32_e32 v29, v10
	v_lshlrev_b32_e32 v10, 16, v11
	v_and_b32_e32 v11, 0xffff0000, v11
	v_pk_mul_f32 v[26:27], v[28:29], v[26:27]
	s_nop 0
	v_pk_mul_f32 v[24:25], v[26:27], v[24:25]
	v_mul_f32_e32 v26, 0xbfb8aa3b, v14
	v_mul_f32_e32 v27, 0xbfb8aa3b, v15
	v_exp_f32_e32 v26, v26
	v_exp_f32_e32 v27, v27
	v_pk_mul_f32 v[24:25], v[6:7], v[24:25]
	v_add_f32_e32 v26, 1.0, v26
	v_add_f32_e32 v27, 1.0, v27
	v_rcp_f32_e32 v26, v26
	v_rcp_f32_e32 v27, v27
	s_nop 0
	v_pk_mul_f32 v[14:15], v[26:27], v[14:15]
	s_nop 0
	v_pk_mul_f32 v[10:11], v[14:15], v[10:11]
	v_lshlrev_b32_e32 v26, 16, v16
	v_pk_mul_f32 v[14:15], v[8:9], v[10:11]
	v_lshlrev_b32_e32 v10, 16, v12
	v_and_b32_e32 v11, 0xffff0000, v12
	v_mul_f32_e32 v12, 0xbfb8aa3b, v26
	v_exp_f32_e32 v12, v12
	v_and_b32_e32 v27, 0xffff0000, v16
	v_add_f32_e32 v12, 1.0, v12
	v_rcp_f32_e32 v28, v12
	v_mul_f32_e32 v12, 0xbfb8aa3b, v27
	v_exp_f32_e32 v12, v12
	s_nop 0
	v_add_f32_e32 v12, 1.0, v12
	v_rcp_f32_e32 v29, v12
	v_lshlrev_b32_e32 v12, 16, v17
	v_mul_f32_e32 v16, 0xbfb8aa3b, v12
	v_exp_f32_e32 v16, v16
	v_pk_mul_f32 v[26:27], v[28:29], v[26:27]
	v_add_f32_e32 v16, 1.0, v16
	v_pk_mul_f32 v[10:11], v[26:27], v[10:11]
	v_rcp_f32_e32 v16, v16
	v_pk_mul_f32 v[26:27], v[2:3], v[10:11]
	v_lshlrev_b32_e32 v10, 16, v13
	v_and_b32_e32 v11, 0xffff0000, v13
	v_and_b32_e32 v13, 0xffff0000, v17
	v_mul_f32_e32 v17, 0xbfb8aa3b, v13
	v_exp_f32_e32 v17, v17
	s_nop 0
	v_add_f32_e32 v17, 1.0, v17
	v_rcp_f32_e32 v17, v17
	s_nop 0
	v_pk_mul_f32 v[12:13], v[16:17], v[12:13]
	s_nop 0
	v_pk_mul_f32 v[10:11], v[12:13], v[10:11]
	v_cvt_pk_bf16_f32 v12, v26, v27
	v_pk_mul_f32 v[16:17], v[4:5], v[10:11]
	v_cvt_pk_bf16_f32 v11, v14, v15
	v_mad_i64_i32 v[14:15], s[4:5], v21, s24, v[18:19]
	v_lshl_add_u64 v[14:15], v[14:15], 0, s[58:59]
	v_cvt_pk_bf16_f32 v10, v24, v25
	v_cvt_pk_bf16_f32 v13, v16, v17
	v_lshl_add_u64 v[14:15], v[14:15], 0, v[0:1]
	global_store_dwordx4 v[14:15], v[10:13], off offset:1024
	s_nop 1
	v_add_u32_e32 v10, 0xc00, v247
	v_ashrrev_i32_e32 v14, 5, v10
	v_mad_u64_u32 v[10:11], s[4:5], v14, s56, v[20:21]
	v_add_u32_e32 v21, s6, v14
	v_mad_i64_i32 v[14:15], s[4:5], v21, s18, v[22:23]
	v_lshl_add_u64 v[14:15], v[14:15], 0, s[58:59]
	v_lshl_add_u64 v[14:15], v[14:15], 0, v[0:1]
	v_add_co_u32_e32 v14, vcc, s23, v14
	ds_read_b128 v[10:13], v10
	s_nop 0
	v_addc_co_u32_e32 v15, vcc, 0, v15, vcc
	v_mov_b64_e32 v[14:15], v[104:105]
	v_mov_b64_e32 v[16:17], v[106:107]
	s_waitcnt lgkmcnt(0)
; #define LAS __attribute__((address_space(3)))
; __device__ __forceinline__ float sigmoidf_(float x) { return __builtin_amdgcn_rcpf(1.0f + __expf(-x)); }
; __device__ __forceinline__ void unpack8(const u32x4 w, float* f) { f[0] = bf_lo(w.x); f[1] = bf_hi(w.x); f[2] = bf_lo(w.y); f[3] = bf_hi(w.y); f[4] = bf_lo(w.z); f[5] = bf_hi(w.z); f[6] = bf_lo(w.w); f[7] = bf_hi(w.w); }
; __device__ __forceinline__ u32x4 pack8(const float* f) { u32x4 w; w.x = cvt_pk_bf16(f[0], f[1]); w.y = cvt_pk_bf16(f[2], f[3]); w.z = cvt_pk_bf16(f[4], f[5]); w.w = cvt_pk_bf16(f[6], f[7]); return w; }
; __device__ __forceinline__ void r3_item(const bf16_t* __restrict__ proj, const bf16_t* __restrict__ projT, const bf16_t* __restrict__ st, bf16_t* ro, ...
;     ...
; #pragma unroll
;     for (int it = 0; it < 8; ++it) { const int id = tid + NTHREADS * it, tq = id >> 5, d8 = (id & 31) * 8;
;         float y[8], rg[8], o[8]; unpack8(*(const LAS u32x4*)(Ol + tq * OL_STRIDE + d8), y);
;         unpack8(__builtin_nontemporal_load((const u32x4*)(proj + (size_t)(tok0 + tq) * NPROJ + 2048 + h * 256 + d8)), rg);
;         const f32x4 g0 = *(const f32x4*)(gn + h * 256 + d8), g1 = *(const f32x4*)(gn + h * 256 + d8 + 4);
; #pragma unroll
;         for (int j = 0; j < 8; ++j) { const float gv = j < 4 ? g0[j & 3] : g1[j & 3]; o[j] = rg[j] * sigmoidf_(rg[j]) * y[j] * gv; }
;         *(u32x4*)(ro + (size_t)(tok0 + tq) * 1536 + 512 + h * 256 + d8) = pack8(o); }
;     __syncthreads();
	v_lshlrev_b32_e32 v24, 16, v10
	v_and_b32_e32 v25, 0xffff0000, v10
	v_lshlrev_b32_e32 v26, 16, v14
	v_mul_f32_e32 v10, 0xbfb8aa3b, v26
	v_exp_f32_e32 v10, v10
	v_and_b32_e32 v27, 0xffff0000, v14
	v_lshlrev_b32_e32 v14, 16, v15
	v_and_b32_e32 v15, 0xffff0000, v15
	v_add_f32_e32 v10, 1.0, v10
	v_rcp_f32_e32 v28, v10
	v_mul_f32_e32 v10, 0xbfb8aa3b, v27
	v_exp_f32_e32 v10, v10
	s_nop 0
	v_add_f32_e32 v10, 1.0, v10
	v_rcp_f32_e32 v29, v10
	v_lshlrev_b32_e32 v10, 16, v11
	v_and_b32_e32 v11, 0xffff0000, v11
	v_pk_mul_f32 v[26:27], v[28:29], v[26:27]
	s_nop 0
	v_pk_mul_f32 v[24:25], v[26:27], v[24:25]
	v_mul_f32_e32 v26, 0xbfb8aa3b, v14
	v_mul_f32_e32 v27, 0xbfb8aa3b, v15
	v_exp_f32_e32 v26, v26
	v_exp_f32_e32 v27, v27
	v_pk_mul_f32 v[24:25], v[6:7], v[24:25]
	v_add_f32_e32 v26, 1.0, v26
	v_add_f32_e32 v27, 1.0, v27
	v_rcp_f32_e32 v26, v26
	v_rcp_f32_e32 v27, v27
	s_nop 0
	v_pk_mul_f32 v[14:15], v[26:27], v[14:15]
	s_nop 0
	v_pk_mul_f32 v[10:11], v[14:15], v[10:11]
	v_lshlrev_b32_e32 v26, 16, v16
	v_pk_mul_f32 v[14:15], v[8:9], v[10:11]
	v_lshlrev_b32_e32 v10, 16, v12
	v_and_b32_e32 v11, 0xffff0000, v12
	v_mul_f32_e32 v12, 0xbfb8aa3b, v26
	v_exp_f32_e32 v12, v12
	v_and_b32_e32 v27, 0xffff0000, v16
	v_add_f32_e32 v12, 1.0, v12
	v_rcp_f32_e32 v28, v12
	v_mul_f32_e32 v12, 0xbfb8aa3b, v27
	v_exp_f32_e32 v12, v12
	s_nop 0
	v_add_f32_e32 v12, 1.0, v12
	v_rcp_f32_e32 v29, v12
	v_lshlrev_b32_e32 v12, 16, v17
	v_mul_f32_e32 v16, 0xbfb8aa3b, v12
	v_exp_f32_e32 v16, v16
	v_pk_mul_f32 v[26:27], v[28:29], v[26:27]
	v_add_f32_e32 v16, 1.0, v16
	v_pk_mul_f32 v[10:11], v[26:27], v[10:11]
	v_rcp_f32_e32 v16, v16
	v_pk_mul_f32 v[26:27], v[2:3], v[10:11]
	v_lshlrev_b32_e32 v10, 16, v13
	v_and_b32_e32 v11, 0xffff0000, v13
	v_and_b32_e32 v13, 0xffff0000, v17
	v_mul_f32_e32 v17, 0xbfb8aa3b, v13
	v_exp_f32_e32 v17, v17
	s_nop 0
	v_add_f32_e32 v17, 1.0, v17
	v_rcp_f32_e32 v17, v17
	s_nop 0
	v_pk_mul_f32 v[12:13], v[16:17], v[12:13]
	s_nop 0
	v_pk_mul_f32 v[10:11], v[12:13], v[10:11]
	v_cvt_pk_bf16_f32 v12, v26, v27
	v_pk_mul_f32 v[16:17], v[4:5], v[10:11]
	v_cvt_pk_bf16_f32 v11, v14, v15
	v_mad_i64_i32 v[14:15], s[4:5], v21, s24, v[18:19]
	v_lshl_add_u64 v[14:15], v[14:15], 0, s[58:59]
	v_cvt_pk_bf16_f32 v10, v24, v25
	v_cvt_pk_bf16_f32 v13, v16, v17
	v_lshl_add_u64 v[14:15], v[14:15], 0, v[0:1]
	global_store_dwordx4 v[14:15], v[10:13], off offset:1024
	s_nop 1
	v_add_u32_e32 v10, 0xe00, v247
	v_ashrrev_i32_e32 v14, 5, v10
	v_mad_u64_u32 v[10:11], s[4:5], v14, s56, v[20:21]
	v_add_u32_e32 v20, s6, v14
	v_mad_i64_i32 v[14:15], s[4:5], v20, s18, v[22:23]
	v_lshl_add_u64 v[14:15], v[14:15], 0, s[58:59]
	v_lshl_add_u64 v[14:15], v[14:15], 0, v[0:1]
	v_add_co_u32_e32 v14, vcc, s23, v14
	ds_read_b128 v[10:13], v10
	s_nop 0
	v_addc_co_u32_e32 v15, vcc, 0, v15, vcc
	v_mov_b64_e32 v[14:15], v[108:109]
	v_mov_b64_e32 v[16:17], v[110:111]
	v_and_b32_e32 v23, 0xffff0000, v16
	v_lshlrev_b32_e32 v22, 16, v16
	v_mul_f32_e32 v16, 0xbfb8aa3b, v23
	v_exp_f32_e32 v16, v16
	s_nop 0
	v_add_f32_e32 v16, 1.0, v16
	v_rcp_f32_e32 v25, v16
	v_mul_f32_e32 v16, 0xbfb8aa3b, v22
	v_exp_f32_e32 v16, v16
	s_nop 0
	v_add_f32_e32 v16, 1.0, v16
	v_rcp_f32_e32 v24, v16
	s_nop 0
	v_pk_mul_f32 v[22:23], v[24:25], v[22:23]
	s_waitcnt lgkmcnt(0)
	v_lshlrev_b32_e32 v24, 16, v12
	v_and_b32_e32 v25, 0xffff0000, v12
	v_pk_mul_f32 v[22:23], v[22:23], v[24:25]
	s_nop 0
	v_pk_mul_f32 v[22:23], v[2:3], v[22:23]
	v_and_b32_e32 v3, 0xffff0000, v15
	v_mul_f32_e32 v12, 0xbfb8aa3b, v3
	v_exp_f32_e32 v12, v12
	v_lshlrev_b32_e32 v2, 16, v15
	v_add_f32_e32 v12, 1.0, v12
	v_rcp_f32_e32 v25, v12
	v_mul_f32_e32 v12, 0xbfb8aa3b, v2
	v_exp_f32_e32 v12, v12
	s_nop 0
	v_add_f32_e32 v12, 1.0, v12
	v_rcp_f32_e32 v24, v12
	v_lshlrev_b32_e32 v12, 16, v13
	v_and_b32_e32 v13, 0xffff0000, v13
	v_pk_mul_f32 v[2:3], v[24:25], v[2:3]
	v_lshlrev_b32_e32 v24, 16, v11
	v_and_b32_e32 v25, 0xffff0000, v11
	v_pk_mul_f32 v[2:3], v[2:3], v[24:25]
	s_nop 0
	v_pk_mul_f32 v[8:9], v[8:9], v[2:3]
	v_and_b32_e32 v3, 0xffff0000, v14
	v_mul_f32_e32 v11, 0xbfb8aa3b, v3
	v_exp_f32_e32 v11, v11
	v_lshlrev_b32_e32 v2, 16, v14
	v_add_f32_e32 v11, 1.0, v11
	v_rcp_f32_e32 v15, v11
	v_mul_f32_e32 v11, 0xbfb8aa3b, v2
	v_exp_f32_e32 v11, v11
	s_nop 0
	v_add_f32_e32 v11, 1.0, v11
	v_rcp_f32_e32 v14, v11
	s_nop 0
	v_pk_mul_f32 v[2:3], v[14:15], v[2:3]
	v_lshlrev_b32_e32 v14, 16, v10
	v_and_b32_e32 v15, 0xffff0000, v10
	v_pk_mul_f32 v[2:3], v[2:3], v[14:15]
	s_nop 0
	v_pk_mul_f32 v[2:3], v[6:7], v[2:3]
	v_lshlrev_b32_e32 v6, 16, v17
	v_and_b32_e32 v7, 0xffff0000, v17
	v_mul_f32_e32 v10, 0xbfb8aa3b, v6
	v_mul_f32_e32 v11, 0xbfb8aa3b, v7
	v_exp_f32_e32 v10, v10
	v_exp_f32_e32 v11, v11
	v_cvt_pk_bf16_f32 v2, v2, v3
	v_cvt_pk_bf16_f32 v3, v8, v9
	v_add_f32_e32 v10, 1.0, v10
	v_add_f32_e32 v11, 1.0, v11
	v_rcp_f32_e32 v10, v10
	v_rcp_f32_e32 v11, v11
	s_nop 0
	v_pk_mul_f32 v[6:7], v[10:11], v[6:7]
	s_nop 0
	v_pk_mul_f32 v[6:7], v[6:7], v[12:13]
	s_nop 0
	v_pk_mul_f32 v[6:7], v[4:5], v[6:7]
	v_cvt_pk_bf16_f32 v4, v22, v23
	v_cvt_pk_bf16_f32 v5, v6, v7
	v_mad_i64_i32 v[6:7], s[4:5], v20, s24, v[18:19]
	v_lshl_add_u64 v[6:7], v[6:7], 0, s[58:59]
	v_lshl_add_u64 v[6:7], v[6:7], 0, v[0:1]
	global_store_dwordx4 v[6:7], v[2:5], off offset:1024
	s_barrier
	s_cbranch_scc1 .LBB0_481
